# P7: the W_down conversion workgroups start ~3.4us late (two s_sleep 64) so the cross-attention units' K/V staging loads are not queued behind the conversion's first load burst
# speedup vs baseline: 1.0705x; 1.0705x over previous
.LBB0_1254:
	s_add_i32 s0, s0, s2
	v_add_u32_e32 v8, s0, v159
	v_cmp_gt_i32_e32 vcc, s5, v8
	s_and_saveexec_b64 s[0:1], vcc
	s_cbranch_execz .LBB0_1257
	v_mul_u32_u24_e32 v0, 0x4100, v159
	v_add_u32_e32 v4, 0, v0
	v_lshlrev_b32_e32 v0, 4, v158
	v_and_b32_e32 v2, 0xf0, v0
	v_mov_b32_e32 v3, 0
	v_lshl_add_u64 v[0:1], s[80:81], 0, v[2:3]
	v_add_u32_e32 v5, v4, v2
	v_lshlrev_b32_e32 v2, 3, v158
	v_bfe_u32 v9, v158, 4, 2
	v_bfe_u32 v10, v158, 3, 3
	v_and_b32_e32 v2, 56, v2
	v_mul_u32_u24_e32 v6, 0x104, v9
	v_mul_u32_u24_e32 v7, 0x104, v2
	v_lshlrev_b32_e32 v2, 1, v2
	v_lshlrev_b32_e32 v11, 2, v10
	v_lshl_add_u64 v[2:3], s[84:85], 0, v[2:3]
	s_mov_b64 s[2:3], 0x3000000
	v_add3_u32 v11, v4, v7, v11
	v_add_u32_e32 v13, v5, v6
	v_lshl_add_u64 v[2:3], v[2:3], 0, s[2:3]
	v_lshlrev_b32_e32 v12, 6, v8
	s_lshl_b32 s6, s4, 6
	s_mov_b64 s[2:3], 0
	v_add_u32_e32 v14, 0x410, v13
	v_add_u32_e32 v15, 0x418, v13
	v_add_u32_e32 v16, 0x820, v13
	v_add_u32_e32 v17, 0x828, v13
	v_add_u32_e32 v18, 0xc30, v13
	v_add_u32_e32 v19, 0xc38, v13
	v_add_u32_e32 v20, 0x1040, v13
	v_add_u32_e32 v21, 0x1048, v13
	v_add_u32_e32 v22, 0x1450, v13
	v_add_u32_e32 v23, 0x1458, v13
	v_add_u32_e32 v24, 0x1860, v13
	v_add_u32_e32 v25, 0x1868, v13
	v_add_u32_e32 v26, 0x1c70, v13
	v_add_u32_e32 v27, 0x1c78, v13
	v_add_u32_e32 v28, 0x2080, v13
	v_add_u32_e32 v29, 0x2088, v13
	v_add_u32_e32 v30, 0x2490, v13
	v_add_u32_e32 v31, 0x2498, v13
	v_add_u32_e32 v32, 0x28a0, v13
	v_add_u32_e32 v33, 0x28a8, v13
	v_add_u32_e32 v34, 0x2cb0, v13
	v_add_u32_e32 v35, 0x2cb8, v13
	v_add_u32_e32 v36, 0x30c0, v13
	v_add_u32_e32 v37, 0x30c8, v13
	v_add_u32_e32 v38, 0x34d0, v13
	v_add_u32_e32 v39, 0x34d8, v13
	v_add_u32_e32 v40, 0x38e0, v13
	v_add_u32_e32 v41, 0x38e8, v13
	v_add_u32_e32 v42, 0x3cf0, v13
	v_add_u32_e32 v43, 0x3cf8, v13
	v_add_u32_e32 v44, 0x400, v11
	s_sleep 64
	s_sleep 64
